# GEMM K-loop: per-segment s_setprio toggling removed (replaced by s_nop, same code size)
# speedup vs baseline: 1.0001x; 1.0001x over previous
.LBB0_702:
	s_add_i32 s47, s4, 2
	s_add_u32 s91, s2, 0x80
	s_addc_u32 s5, s3, 0
	s_add_i32 s93, 0, 0x10000
	s_cmp_eq_u32 s31, s4
	s_cselect_b32 s5, s87, s5
	s_cselect_b32 s4, s86, s91
	s_cselect_b32 s95, s89, s46
	s_cselect_b32 s94, s88, s7
	s_add_i32 s91, 0, 0x14000
	v_add_u32_e32 v140, s93, v195
	v_add_u32_e32 v156, s91, v195
	ds_read_b128 v[128:131], v140
	ds_read_b128 v[132:135], v140 offset:1024
	ds_read_b128 v[136:139], v140 offset:2048
	ds_read_b128 v[140:143], v140 offset:3072
	ds_read_b128 v[144:147], v156
	ds_read_b128 v[148:151], v156 offset:1024
	ds_read_b128 v[152:155], v156 offset:2048
	ds_read_b128 v[156:159], v156 offset:3072
	v_lshl_add_u64 v[208:209], s[2:3], 0, v[204:205]
	s_add_i32 m0, s20, 0xc000
	ds_read_b128 v[160:163], v246
	ds_read_b128 v[164:167], v246 offset:1024
	ds_read_b128 v[168:171], v246 offset:2048
	ds_read_b128 v[172:175], v246 offset:3072
	ds_read_b128 v[176:179], v246 offset:4096
	ds_read_b128 v[180:183], v246 offset:5120
	ds_read_b128 v[184:187], v246 offset:6144
	ds_read_b128 v[188:191], v246 offset:7168
	global_load_lds_dwordx4 v[208:209], off
	v_lshl_add_u64 v[208:209], s[2:3], 0, v[206:207]
	s_add_i32 m0, s20, 0xe000
	s_nop 0
	global_load_lds_dwordx4 v[208:209], off
	s_waitcnt vmcnt(8)
	s_waitcnt lgkmcnt(0)
	s_barrier
	s_nop 0
	s_waitcnt lgkmcnt(0)
	v_mfma_f32_16x16x32_bf16 v[124:127], v[128:131], v[160:163], v[124:127]
	v_mfma_f32_16x16x32_bf16 v[60:63], v[136:139], v[160:163], v[60:63]
	v_mfma_f32_16x16x32_bf16 v[116:119], v[128:131], v[168:171], v[116:119]
	v_mfma_f32_16x16x32_bf16 v[52:55], v[136:139], v[168:171], v[52:55]
	v_mfma_f32_16x16x32_bf16 v[108:111], v[128:131], v[176:179], v[108:111]
	v_mfma_f32_16x16x32_bf16 v[44:47], v[136:139], v[176:179], v[44:47]
	v_mfma_f32_16x16x32_bf16 v[100:103], v[128:131], v[184:187], v[100:103]
	v_mfma_f32_16x16x32_bf16 v[36:39], v[136:139], v[184:187], v[36:39]
	v_mfma_f32_16x16x32_bf16 v[124:127], v[132:135], v[164:167], v[124:127]
	v_mfma_f32_16x16x32_bf16 v[60:63], v[140:143], v[164:167], v[60:63]
	v_mfma_f32_16x16x32_bf16 v[116:119], v[132:135], v[172:175], v[116:119]
	v_mfma_f32_16x16x32_bf16 v[52:55], v[140:143], v[172:175], v[52:55]
	v_mfma_f32_16x16x32_bf16 v[108:111], v[132:135], v[180:183], v[108:111]
	v_mfma_f32_16x16x32_bf16 v[44:47], v[140:143], v[180:183], v[44:47]
	v_mfma_f32_16x16x32_bf16 v[100:103], v[132:135], v[188:191], v[100:103]
	v_mfma_f32_16x16x32_bf16 v[36:39], v[140:143], v[188:191], v[36:39]
	s_nop 0
	s_nop 0
	v_mfma_f32_16x16x32_bf16 v[120:123], v[144:147], v[160:163], v[120:123]
	v_mfma_f32_16x16x32_bf16 v[56:59], v[152:155], v[160:163], v[56:59]
	v_mfma_f32_16x16x32_bf16 v[112:115], v[144:147], v[168:171], v[112:115]
	v_mfma_f32_16x16x32_bf16 v[48:51], v[152:155], v[168:171], v[48:51]
	v_mfma_f32_16x16x32_bf16 v[104:107], v[144:147], v[176:179], v[104:107]
	v_mfma_f32_16x16x32_bf16 v[40:43], v[152:155], v[176:179], v[40:43]
	v_mfma_f32_16x16x32_bf16 v[96:99], v[144:147], v[184:187], v[96:99]
	v_mfma_f32_16x16x32_bf16 v[32:35], v[152:155], v[184:187], v[32:35]
	v_mfma_f32_16x16x32_bf16 v[120:123], v[148:151], v[164:167], v[120:123]
	v_mfma_f32_16x16x32_bf16 v[56:59], v[156:159], v[164:167], v[56:59]
	v_mfma_f32_16x16x32_bf16 v[112:115], v[148:151], v[172:175], v[112:115]
	v_mfma_f32_16x16x32_bf16 v[48:51], v[156:159], v[172:175], v[48:51]
	v_mfma_f32_16x16x32_bf16 v[104:107], v[148:151], v[180:183], v[104:107]
	v_mfma_f32_16x16x32_bf16 v[40:43], v[156:159], v[180:183], v[40:43]
	v_mfma_f32_16x16x32_bf16 v[96:99], v[148:151], v[188:191], v[96:99]
	v_mfma_f32_16x16x32_bf16 v[32:35], v[156:159], v[188:191], v[32:35]
	s_nop 0
	s_barrier
	s_add_i32 s93, s93, s83
	v_lshl_add_u64 v[208:209], s[94:95], 0, v[202:203]
	s_mov_b32 m0, s93
	ds_read_b128 v[160:163], v246 offset:16384
	ds_read_b128 v[164:167], v246 offset:17408
	ds_read_b128 v[168:171], v246 offset:18432
	ds_read_b128 v[172:175], v246 offset:19456
	ds_read_b128 v[176:179], v246 offset:20480
	ds_read_b128 v[180:183], v246 offset:21504
	ds_read_b128 v[184:187], v246 offset:22528
	ds_read_b128 v[188:191], v246 offset:23552
	global_load_lds_dwordx4 v[208:209], off
	s_add_i32 m0, s93, 0x2000
	v_lshl_add_u64 v[210:211], s[94:95], 0, v[198:199]
	s_add_u32 s94, s94, s50
	s_addc_u32 s95, s95, s51
	s_add_i32 s91, s91, s83
	global_load_lds_dwordx4 v[210:211], off
	v_lshl_add_u64 v[212:213], s[94:95], 0, v[202:203]
	s_mov_b32 m0, s91
	v_lshl_add_u64 v[214:215], s[94:95], 0, v[198:199]
	global_load_lds_dwordx4 v[212:213], off
	s_add_i32 m0, s91, 0x2000
	v_lshl_add_u64 v[216:217], s[4:5], 0, v[200:201]
	global_load_lds_dwordx4 v[214:215], off
	s_mov_b32 m0, s20
	v_lshl_add_u64 v[218:219], s[4:5], 0, v[196:197]
	global_load_lds_dwordx4 v[216:217], off
	s_mov_b32 m0, s21
	s_nop 0
	global_load_lds_dwordx4 v[218:219], off
	s_waitcnt vmcnt(8)
	s_waitcnt lgkmcnt(0)
	s_barrier
	s_nop 0
	s_waitcnt lgkmcnt(0)
	v_mfma_f32_16x16x32_bf16 v[92:95], v[128:131], v[160:163], v[92:95]
	v_mfma_f32_16x16x32_bf16 v[28:31], v[136:139], v[160:163], v[28:31]
	v_mfma_f32_16x16x32_bf16 v[84:87], v[128:131], v[168:171], v[84:87]
	v_mfma_f32_16x16x32_bf16 v[20:23], v[136:139], v[168:171], v[20:23]
	v_mfma_f32_16x16x32_bf16 v[76:79], v[128:131], v[176:179], v[76:79]
	v_mfma_f32_16x16x32_bf16 v[12:15], v[136:139], v[176:179], v[12:15]
	v_mfma_f32_16x16x32_bf16 v[68:71], v[128:131], v[184:187], v[68:71]
	v_mfma_f32_16x16x32_bf16 v[4:7], v[136:139], v[184:187], v[4:7]
	v_mfma_f32_16x16x32_bf16 v[92:95], v[132:135], v[164:167], v[92:95]
	v_mfma_f32_16x16x32_bf16 v[28:31], v[140:143], v[164:167], v[28:31]
	v_mfma_f32_16x16x32_bf16 v[84:87], v[132:135], v[172:175], v[84:87]
	v_mfma_f32_16x16x32_bf16 v[20:23], v[140:143], v[172:175], v[20:23]
	v_mfma_f32_16x16x32_bf16 v[76:79], v[132:135], v[180:183], v[76:79]
	v_mfma_f32_16x16x32_bf16 v[12:15], v[140:143], v[180:183], v[12:15]
	v_mfma_f32_16x16x32_bf16 v[68:71], v[132:135], v[188:191], v[68:71]
	v_mfma_f32_16x16x32_bf16 v[4:7], v[140:143], v[188:191], v[4:7]
	s_nop 0
	s_nop 0
	v_mfma_f32_16x16x32_bf16 v[88:91], v[144:147], v[160:163], v[88:91]
	v_mfma_f32_16x16x32_bf16 v[24:27], v[152:155], v[160:163], v[24:27]
	v_mfma_f32_16x16x32_bf16 v[80:83], v[144:147], v[168:171], v[80:83]
	v_mfma_f32_16x16x32_bf16 v[16:19], v[152:155], v[168:171], v[16:19]
	v_mfma_f32_16x16x32_bf16 v[72:75], v[144:147], v[176:179], v[72:75]
	v_mfma_f32_16x16x32_bf16 v[8:11], v[152:155], v[176:179], v[8:11]
	v_mfma_f32_16x16x32_bf16 v[64:67], v[144:147], v[184:187], v[64:67]
	v_mfma_f32_16x16x32_bf16 v[0:3], v[152:155], v[184:187], v[0:3]
	v_mfma_f32_16x16x32_bf16 v[88:91], v[148:151], v[164:167], v[88:91]
	v_mfma_f32_16x16x32_bf16 v[24:27], v[156:159], v[164:167], v[24:27]
	v_mfma_f32_16x16x32_bf16 v[80:83], v[148:151], v[172:175], v[80:83]
	v_mfma_f32_16x16x32_bf16 v[16:19], v[156:159], v[172:175], v[16:19]
	v_mfma_f32_16x16x32_bf16 v[72:75], v[148:151], v[180:183], v[72:75]
	v_mfma_f32_16x16x32_bf16 v[8:11], v[156:159], v[180:183], v[8:11]
	v_mfma_f32_16x16x32_bf16 v[64:67], v[148:151], v[188:191], v[64:67]
	v_mfma_f32_16x16x32_bf16 v[0:3], v[156:159], v[188:191], v[0:3]
	s_nop 0
	s_barrier
	v_add_u32_e32 v140, s17, v195
	v_add_u32_e32 v156, s66, v195
	ds_read_b128 v[128:131], v140
	ds_read_b128 v[132:135], v140 offset:1024
	ds_read_b128 v[136:139], v140 offset:2048
	ds_read_b128 v[140:143], v140 offset:3072
	ds_read_b128 v[144:147], v156
	ds_read_b128 v[148:151], v156 offset:1024
	ds_read_b128 v[152:155], v156 offset:2048
	ds_read_b128 v[156:159], v156 offset:3072
	s_add_u32 s4, s4, s50
	s_addc_u32 s5, s5, s51
	s_mov_b32 m0, s26
	v_lshl_add_u64 v[220:221], s[4:5], 0, v[200:201]
	ds_read_b128 v[160:163], v246 offset:32768
	ds_read_b128 v[164:167], v246 offset:33792
	ds_read_b128 v[168:171], v246 offset:34816
	ds_read_b128 v[172:175], v246 offset:35840
	ds_read_b128 v[176:179], v246 offset:36864
	ds_read_b128 v[180:183], v246 offset:37888
	ds_read_b128 v[184:187], v246 offset:38912
	ds_read_b128 v[188:191], v246 offset:39936
	global_load_lds_dwordx4 v[220:221], off
	v_lshl_add_u64 v[220:221], s[4:5], 0, v[196:197]
	s_mov_b32 m0, s27
	s_nop 0
	global_load_lds_dwordx4 v[220:221], off
	s_waitcnt vmcnt(8)
	s_waitcnt lgkmcnt(0)
	s_barrier
	s_nop 0
	s_waitcnt lgkmcnt(0)
	v_mfma_f32_16x16x32_bf16 v[124:127], v[128:131], v[160:163], v[124:127]
	v_mfma_f32_16x16x32_bf16 v[60:63], v[136:139], v[160:163], v[60:63]
	v_mfma_f32_16x16x32_bf16 v[116:119], v[128:131], v[168:171], v[116:119]
	v_mfma_f32_16x16x32_bf16 v[52:55], v[136:139], v[168:171], v[52:55]
	v_mfma_f32_16x16x32_bf16 v[108:111], v[128:131], v[176:179], v[108:111]
	v_mfma_f32_16x16x32_bf16 v[44:47], v[136:139], v[176:179], v[44:47]
	v_mfma_f32_16x16x32_bf16 v[100:103], v[128:131], v[184:187], v[100:103]
	v_mfma_f32_16x16x32_bf16 v[36:39], v[136:139], v[184:187], v[36:39]
	v_mfma_f32_16x16x32_bf16 v[124:127], v[132:135], v[164:167], v[124:127]
	v_mfma_f32_16x16x32_bf16 v[60:63], v[140:143], v[164:167], v[60:63]
	v_mfma_f32_16x16x32_bf16 v[116:119], v[132:135], v[172:175], v[116:119]
	v_mfma_f32_16x16x32_bf16 v[52:55], v[140:143], v[172:175], v[52:55]
	v_mfma_f32_16x16x32_bf16 v[108:111], v[132:135], v[180:183], v[108:111]
	v_mfma_f32_16x16x32_bf16 v[44:47], v[140:143], v[180:183], v[44:47]
	v_mfma_f32_16x16x32_bf16 v[100:103], v[132:135], v[188:191], v[100:103]
	v_mfma_f32_16x16x32_bf16 v[36:39], v[140:143], v[188:191], v[36:39]
	s_nop 0
	s_nop 0
	v_mfma_f32_16x16x32_bf16 v[120:123], v[144:147], v[160:163], v[120:123]
	v_mfma_f32_16x16x32_bf16 v[56:59], v[152:155], v[160:163], v[56:59]
	v_mfma_f32_16x16x32_bf16 v[112:115], v[144:147], v[168:171], v[112:115]
	v_mfma_f32_16x16x32_bf16 v[48:51], v[152:155], v[168:171], v[48:51]
	v_mfma_f32_16x16x32_bf16 v[104:107], v[144:147], v[176:179], v[104:107]
	v_mfma_f32_16x16x32_bf16 v[40:43], v[152:155], v[176:179], v[40:43]
	v_mfma_f32_16x16x32_bf16 v[96:99], v[144:147], v[184:187], v[96:99]
	v_mfma_f32_16x16x32_bf16 v[32:35], v[152:155], v[184:187], v[32:35]
	v_mfma_f32_16x16x32_bf16 v[120:123], v[148:151], v[164:167], v[120:123]
	v_mfma_f32_16x16x32_bf16 v[56:59], v[156:159], v[164:167], v[56:59]
	v_mfma_f32_16x16x32_bf16 v[112:115], v[148:151], v[172:175], v[112:115]
	v_mfma_f32_16x16x32_bf16 v[48:51], v[156:159], v[172:175], v[48:51]
	v_mfma_f32_16x16x32_bf16 v[104:107], v[148:151], v[180:183], v[104:107]
	v_mfma_f32_16x16x32_bf16 v[40:43], v[156:159], v[180:183], v[40:43]
	v_mfma_f32_16x16x32_bf16 v[96:99], v[148:151], v[188:191], v[96:99]
	v_mfma_f32_16x16x32_bf16 v[32:35], v[156:159], v[188:191], v[32:35]
	s_nop 0
	s_barrier
	s_add_i32 s4, s17, s83
	v_lshl_add_u64 v[208:209], v[208:209], 0, s[38:39]
	s_mov_b32 m0, s4
	ds_read_b128 v[160:163], v246 offset:49152
	ds_read_b128 v[164:167], v246 offset:50176
	ds_read_b128 v[168:171], v246 offset:51200
	ds_read_b128 v[172:175], v246 offset:52224
	ds_read_b128 v[176:179], v246 offset:53248
	ds_read_b128 v[180:183], v246 offset:54272
	ds_read_b128 v[184:187], v246 offset:55296
	ds_read_b128 v[188:191], v246 offset:56320
	global_load_lds_dwordx4 v[208:209], off
	v_lshl_add_u64 v[208:209], v[210:211], 0, s[38:39]
	s_add_i32 m0, s4, 0x2000
	s_add_i32 s4, s66, s83
	global_load_lds_dwordx4 v[208:209], off
	v_lshl_add_u64 v[208:209], v[212:213], 0, s[38:39]
	s_mov_b32 m0, s4
	s_nop 0
	global_load_lds_dwordx4 v[208:209], off
	v_lshl_add_u64 v[208:209], v[214:215], 0, s[38:39]
	s_add_i32 m0, s4, 0x2000
	s_nop 0
	global_load_lds_dwordx4 v[208:209], off
	v_lshl_add_u64 v[208:209], v[216:217], 0, s[38:39]
	s_mov_b32 m0, s54
	s_nop 0
	global_load_lds_dwordx4 v[208:209], off
	v_lshl_add_u64 v[208:209], v[218:219], 0, s[38:39]
	s_mov_b32 m0, s55
	s_nop 0
	global_load_lds_dwordx4 v[208:209], off
	s_waitcnt vmcnt(8)
	s_waitcnt lgkmcnt(0)
	s_barrier
	s_nop 0
	s_waitcnt lgkmcnt(0)
	v_mfma_f32_16x16x32_bf16 v[92:95], v[128:131], v[160:163], v[92:95]
	v_mfma_f32_16x16x32_bf16 v[28:31], v[136:139], v[160:163], v[28:31]
	v_mfma_f32_16x16x32_bf16 v[84:87], v[128:131], v[168:171], v[84:87]
	v_mfma_f32_16x16x32_bf16 v[20:23], v[136:139], v[168:171], v[20:23]
	v_mfma_f32_16x16x32_bf16 v[76:79], v[128:131], v[176:179], v[76:79]
	v_mfma_f32_16x16x32_bf16 v[12:15], v[136:139], v[176:179], v[12:15]
	v_mfma_f32_16x16x32_bf16 v[68:71], v[128:131], v[184:187], v[68:71]
	v_mfma_f32_16x16x32_bf16 v[4:7], v[136:139], v[184:187], v[4:7]
	v_mfma_f32_16x16x32_bf16 v[92:95], v[132:135], v[164:167], v[92:95]
	v_mfma_f32_16x16x32_bf16 v[28:31], v[140:143], v[164:167], v[28:31]
	v_mfma_f32_16x16x32_bf16 v[84:87], v[132:135], v[172:175], v[84:87]
	v_mfma_f32_16x16x32_bf16 v[20:23], v[140:143], v[172:175], v[20:23]
	v_mfma_f32_16x16x32_bf16 v[76:79], v[132:135], v[180:183], v[76:79]
	v_mfma_f32_16x16x32_bf16 v[12:15], v[140:143], v[180:183], v[12:15]
	v_mfma_f32_16x16x32_bf16 v[68:71], v[132:135], v[188:191], v[68:71]
	v_mfma_f32_16x16x32_bf16 v[4:7], v[140:143], v[188:191], v[4:7]
	s_nop 0
	s_nop 0
	v_mfma_f32_16x16x32_bf16 v[88:91], v[144:147], v[160:163], v[88:91]
	v_mfma_f32_16x16x32_bf16 v[24:27], v[152:155], v[160:163], v[24:27]
	v_mfma_f32_16x16x32_bf16 v[80:83], v[144:147], v[168:171], v[80:83]
	v_mfma_f32_16x16x32_bf16 v[16:19], v[152:155], v[168:171], v[16:19]
	v_mfma_f32_16x16x32_bf16 v[72:75], v[144:147], v[176:179], v[72:75]
	v_mfma_f32_16x16x32_bf16 v[8:11], v[152:155], v[176:179], v[8:11]
	v_mfma_f32_16x16x32_bf16 v[64:67], v[144:147], v[184:187], v[64:67]
	v_mfma_f32_16x16x32_bf16 v[0:3], v[152:155], v[184:187], v[0:3]
	v_mfma_f32_16x16x32_bf16 v[88:91], v[148:151], v[164:167], v[88:91]
	v_mfma_f32_16x16x32_bf16 v[24:27], v[156:159], v[164:167], v[24:27]
	v_mfma_f32_16x16x32_bf16 v[80:83], v[148:151], v[172:175], v[80:83]
	v_mfma_f32_16x16x32_bf16 v[16:19], v[156:159], v[172:175], v[16:19]
	v_mfma_f32_16x16x32_bf16 v[72:75], v[148:151], v[180:183], v[72:75]
	v_mfma_f32_16x16x32_bf16 v[8:11], v[156:159], v[180:183], v[8:11]
	v_mfma_f32_16x16x32_bf16 v[64:67], v[148:151], v[188:191], v[64:67]
	v_mfma_f32_16x16x32_bf16 v[0:3], v[156:159], v[188:191], v[0:3]
	s_nop 0
	s_barrier
	s_add_u32 s2, s2, 0x100
	s_addc_u32 s3, s3, 0
	s_add_u32 s7, s7, 0x100
	s_addc_u32 s46, s46, 0
	s_cmp_ge_u32 s47, s56
	s_mov_b32 s4, s47
	s_cbranch_scc0 .LBB0_702
	s_and_b64 vcc, exec, s[0:1]
	s_cbranch_vccz .LBB0_705
	s_barrier
